# speedup vs baseline: 1.0084x; 1.0084x over previous
; __device__ __forceinline__ unsigned pk2(float lo, float hi) { const f32x2_t v = {lo, hi}; return __builtin_bit_cast(unsigned, __builtin_convertvector(v, bf16x2_t)); }
; template <int A0, int A1, int B0, int B1, bool LOC> ...
;     ...
;     float ps = 0.f;
; #pragma unroll
;     for (int i = 0; i < 16; ++i) { if (i >= A0 && i < A1) { s0[i] = __builtin_amdgcn_exp2f(s0[i] - mn); ps += s0[i]; } else s0[i] = 0.f; }
; #pragma unroll
;     for (int i = 0; i < 16; ++i) { if (i >= B0 && i < B1) { s1v[i] = __builtin_amdgcn_exp2f(s1v[i] - mn); ps += s1v[i]; } else s1v[i] = 0.f; }
;     lsum += ps;
; #pragma unroll
;     for (int kk = 0; kk < 4; ++kk) {
;         const int o = 8 * (kk & 1); const bool live = (kk < 2) ? (o < A1 && o + 8 > A0) : (o < B1 && o + 8 > B0);
;         if (!live) continue;
;         u32x4 pw;
;         if (kk < 2) { pw.x = pk2(s0[o], s0[o + 1]); pw.y = pk2(s0[o + 2], s0[o + 3]); pw.z = pk2(s0[o + 4], s0[o + 5]); pw.w = pk2(s0[o + 6], s0[o + 7]); }
;         else { pw.x = pk2(s1v[o], s1v[o + 1]); pw.y = pk2(s1v[o + 2], s1v[o + 3]); pw.z = pk2(s1v[o + 4], s1v[o + 5]); pw.w = pk2(s1v[o + 6], s1v[o + 7]); }
;         const bf16x8 pf = __builtin_bit_cast(bf16x8, pw);
;         const bf16x8 v0 = tr2(vbuf + kk * 2048 + vro + ((0 ^ vsw) * 64), 1024), v1 = tr2(vbuf + kk * 2048 + vro + ((1 ^ vsw) * 64), 1024);
;         o0 = __builtin_amdgcn_mfma_f32_32x32x16_bf16(v0, pf, o0, 0, 0, 0);
;         o1 = __builtin_amdgcn_mfma_f32_32x32x16_bf16(v1, pf, o1, 0, 0, 0);
;     }
.LBB0_499:
	v_pk_add_f32 v[52:53], v[52:53], v[194:195] op_sel:[0,1] op_sel_hi:[1,1] neg_lo:[0,1] neg_hi:[0,1]
	v_pk_add_f32 v[54:55], v[54:55], v[194:195] op_sel:[0,1] op_sel_hi:[1,1] neg_lo:[0,1] neg_hi:[0,1]
	v_pk_add_f32 v[56:57], v[56:57], v[194:195] op_sel:[0,1] op_sel_hi:[1,1] neg_lo:[0,1] neg_hi:[0,1]
	v_pk_add_f32 v[58:59], v[58:59], v[194:195] op_sel:[0,1] op_sel_hi:[1,1] neg_lo:[0,1] neg_hi:[0,1]
	v_pk_add_f32 v[60:61], v[60:61], v[194:195] op_sel:[0,1] op_sel_hi:[1,1] neg_lo:[0,1] neg_hi:[0,1]
	v_pk_add_f32 v[62:63], v[62:63], v[194:195] op_sel:[0,1] op_sel_hi:[1,1] neg_lo:[0,1] neg_hi:[0,1]
	v_pk_add_f32 v[64:65], v[64:65], v[194:195] op_sel:[0,1] op_sel_hi:[1,1] neg_lo:[0,1] neg_hi:[0,1]
	v_pk_add_f32 v[66:67], v[66:67], v[194:195] op_sel:[0,1] op_sel_hi:[1,1] neg_lo:[0,1] neg_hi:[0,1]
	v_pk_add_f32 v[36:37], v[36:37], v[194:195] op_sel:[0,1] op_sel_hi:[1,1] neg_lo:[0,1] neg_hi:[0,1]
	v_pk_add_f32 v[38:39], v[38:39], v[194:195] op_sel:[0,1] op_sel_hi:[1,1] neg_lo:[0,1] neg_hi:[0,1]
	v_pk_add_f32 v[40:41], v[40:41], v[194:195] op_sel:[0,1] op_sel_hi:[1,1] neg_lo:[0,1] neg_hi:[0,1]
	v_pk_add_f32 v[42:43], v[42:43], v[194:195] op_sel:[0,1] op_sel_hi:[1,1] neg_lo:[0,1] neg_hi:[0,1]
	v_pk_add_f32 v[44:45], v[44:45], v[194:195] op_sel:[0,1] op_sel_hi:[1,1] neg_lo:[0,1] neg_hi:[0,1]
	v_pk_add_f32 v[46:47], v[46:47], v[194:195] op_sel:[0,1] op_sel_hi:[1,1] neg_lo:[0,1] neg_hi:[0,1]
	v_pk_add_f32 v[48:49], v[48:49], v[194:195] op_sel:[0,1] op_sel_hi:[1,1] neg_lo:[0,1] neg_hi:[0,1]
	v_pk_add_f32 v[50:51], v[50:51], v[194:195] op_sel:[0,1] op_sel_hi:[1,1] neg_lo:[0,1] neg_hi:[0,1]
	v_exp_f32_e32 v52, v52
	v_exp_f32_e32 v53, v53
	v_exp_f32_e32 v54, v54
	v_add_f32_e32 v3, v53, v52
	v_exp_f32_e32 v55, v55
	v_add_f32_e32 v3, v54, v3
	v_exp_f32_e32 v56, v56
	v_add_f32_e32 v3, v55, v3
	v_exp_f32_e32 v57, v57
	v_add_f32_e32 v3, v56, v3
	v_exp_f32_e32 v58, v58
	v_add_f32_e32 v3, v57, v3
	v_exp_f32_e32 v59, v59
	v_add_f32_e32 v3, v58, v3
	v_exp_f32_e32 v60, v60
	v_add_f32_e32 v3, v59, v3
	v_exp_f32_e32 v61, v61
	v_add_f32_e32 v3, v60, v3
	v_exp_f32_e32 v62, v62
	v_add_f32_e32 v3, v61, v3
	v_exp_f32_e32 v63, v63
	v_add_f32_e32 v3, v62, v3
	v_exp_f32_e32 v64, v64
	v_add_f32_e32 v3, v63, v3
	v_exp_f32_e32 v65, v65
	v_add_f32_e32 v3, v64, v3
	v_exp_f32_e32 v66, v66
	v_add_f32_e32 v3, v65, v3
	v_exp_f32_e32 v67, v67
	v_add_f32_e32 v3, v66, v3
	v_exp_f32_e32 v36, v36
	v_add_f32_e32 v3, v67, v3
	v_exp_f32_e32 v37, v37
	v_add_f32_e32 v3, v36, v3
	v_exp_f32_e32 v38, v38
	v_add_f32_e32 v3, v37, v3
	v_exp_f32_e32 v39, v39
	v_add_f32_e32 v3, v38, v3
	v_exp_f32_e32 v40, v40
	v_add_f32_e32 v3, v39, v3
	v_exp_f32_e32 v41, v41
	v_add_f32_e32 v3, v40, v3
	v_exp_f32_e32 v42, v42
	v_add_f32_e32 v3, v41, v3
	v_exp_f32_e32 v43, v43
	v_add_f32_e32 v3, v42, v3
	v_exp_f32_e32 v44, v44
	v_add_f32_e32 v3, v43, v3
	v_exp_f32_e32 v45, v45
	v_add_f32_e32 v3, v44, v3
	v_exp_f32_e32 v46, v46
	v_add_f32_e32 v3, v45, v3
	v_exp_f32_e32 v47, v47
	v_add_f32_e32 v3, v46, v3
	v_exp_f32_e32 v48, v48
	v_add_f32_e32 v3, v47, v3
	v_exp_f32_e32 v49, v49
	v_add_f32_e32 v3, v48, v3
	v_exp_f32_e32 v50, v50
	v_add_f32_e32 v3, v49, v3
	v_exp_f32_e32 v51, v51
	v_add_f32_e32 v3, v50, v3
	v_add_u32_e32 v0, v183, v184
	v_add_u32_e32 v1, v183, v185
	v_add_f32_e32 v3, v51, v3
	v_add_f32_e32 v196, v3, v141
	ds_read_b64_tr_b16 v[72:73], v0 offset:32768
	ds_read_b64_tr_b16 v[74:75], v0 offset:33792
	ds_read_b64_tr_b16 v[76:77], v1 offset:32768
	ds_read_b64_tr_b16 v[78:79], v1 offset:33792
	v_cvt_pk_bf16_f32 v68, v52, v53
	v_cvt_pk_bf16_f32 v69, v54, v55
	v_cvt_pk_bf16_f32 v70, v56, v57
	v_cvt_pk_bf16_f32 v71, v58, v59
	s_waitcnt lgkmcnt(0)
	s_nop 0
	v_mfma_f32_32x32x16_bf16 v[20:35], v[72:75], v[68:71], v[20:35]
	v_mfma_f32_32x32x16_bf16 v[4:19], v[76:79], v[68:71], v[4:19]
	ds_read_b64_tr_b16 v[72:73], v0 offset:34816
	ds_read_b64_tr_b16 v[74:75], v0 offset:35840
	ds_read_b64_tr_b16 v[76:77], v1 offset:34816
	ds_read_b64_tr_b16 v[78:79], v1 offset:35840
	v_cvt_pk_bf16_f32 v68, v60, v61
	v_cvt_pk_bf16_f32 v69, v62, v63
	v_cvt_pk_bf16_f32 v70, v64, v65
	v_cvt_pk_bf16_f32 v71, v66, v67
	s_waitcnt lgkmcnt(0)
	s_nop 0
	v_mfma_f32_32x32x16_bf16 v[20:35], v[72:75], v[68:71], v[20:35]
	v_mfma_f32_32x32x16_bf16 v[4:19], v[76:79], v[68:71], v[4:19]
	ds_read_b64_tr_b16 v[72:73], v0 offset:36864
	ds_read_b64_tr_b16 v[74:75], v0 offset:37888
	ds_read_b64_tr_b16 v[76:77], v1 offset:36864
	ds_read_b64_tr_b16 v[78:79], v1 offset:37888
	v_cvt_pk_bf16_f32 v68, v36, v37
	v_cvt_pk_bf16_f32 v69, v38, v39
	v_cvt_pk_bf16_f32 v70, v40, v41
	v_cvt_pk_bf16_f32 v71, v42, v43
	s_waitcnt lgkmcnt(0)
	s_nop 0
	v_mfma_f32_32x32x16_bf16 v[20:35], v[72:75], v[68:71], v[20:35]
	v_mfma_f32_32x32x16_bf16 v[4:19], v[76:79], v[68:71], v[4:19]
	ds_read_b64_tr_b16 v[72:73], v0 offset:38912
	ds_read_b64_tr_b16 v[74:75], v0 offset:39936
	ds_read_b64_tr_b16 v[76:77], v1 offset:38912
	ds_read_b64_tr_b16 v[78:79], v1 offset:39936
	v_cvt_pk_bf16_f32 v68, v44, v45
	v_cvt_pk_bf16_f32 v69, v46, v47
	v_cvt_pk_bf16_f32 v70, v48, v49
	v_cvt_pk_bf16_f32 v71, v50, v51
	s_waitcnt lgkmcnt(0)
	s_nop 0
	v_mfma_f32_32x32x16_bf16 v[20:35], v[72:75], v[68:71], v[20:35]
	v_mfma_f32_32x32x16_bf16 v[4:19], v[76:79], v[68:71], v[4:19]

; __device__ __forceinline__ unsigned pk2(float lo, float hi) { const f32x2_t v = {lo, hi}; return __builtin_bit_cast(unsigned, __builtin_convertvector(v, bf16x2_t)); }
; template <int A0, int A1, int B0, int B1, bool LOC> ...
;     ...
;     float ps = 0.f;
; #pragma unroll
;     for (int i = 0; i < 16; ++i) { if (i >= A0 && i < A1) { s0[i] = __builtin_amdgcn_exp2f(s0[i] - mn); ps += s0[i]; } else s0[i] = 0.f; }
; #pragma unroll
;     for (int i = 0; i < 16; ++i) { if (i >= B0 && i < B1) { s1v[i] = __builtin_amdgcn_exp2f(s1v[i] - mn); ps += s1v[i]; } else s1v[i] = 0.f; }
;     lsum += ps;
; #pragma unroll
;     for (int kk = 0; kk < 4; ++kk) {
;         const int o = 8 * (kk & 1); const bool live = (kk < 2) ? (o < A1 && o + 8 > A0) : (o < B1 && o + 8 > B0);
;         if (!live) continue;
;         u32x4 pw;
;         if (kk < 2) { pw.x = pk2(s0[o], s0[o + 1]); pw.y = pk2(s0[o + 2], s0[o + 3]); pw.z = pk2(s0[o + 4], s0[o + 5]); pw.w = pk2(s0[o + 6], s0[o + 7]); }
;         else { pw.x = pk2(s1v[o], s1v[o + 1]); pw.y = pk2(s1v[o + 2], s1v[o + 3]); pw.z = pk2(s1v[o + 4], s1v[o + 5]); pw.w = pk2(s1v[o + 6], s1v[o + 7]); }
;         const bf16x8 pf = __builtin_bit_cast(bf16x8, pw);
;         const bf16x8 v0 = tr2(vbuf + kk * 2048 + vro + ((0 ^ vsw) * 64), 1024), v1 = tr2(vbuf + kk * 2048 + vro + ((1 ^ vsw) * 64), 1024);
;         o0 = __builtin_amdgcn_mfma_f32_32x32x16_bf16(v0, pf, o0, 0, 0, 0);
;         o1 = __builtin_amdgcn_mfma_f32_32x32x16_bf16(v1, pf, o1, 0, 0, 0);
;     }
.LBB0_523:
	v_pk_add_f32 v[52:53], v[52:53], v[194:195] op_sel:[0,1] op_sel_hi:[1,1] neg_lo:[0,1] neg_hi:[0,1]
	v_pk_add_f32 v[54:55], v[54:55], v[194:195] op_sel:[0,1] op_sel_hi:[1,1] neg_lo:[0,1] neg_hi:[0,1]
	v_pk_add_f32 v[56:57], v[56:57], v[194:195] op_sel:[0,1] op_sel_hi:[1,1] neg_lo:[0,1] neg_hi:[0,1]
	v_pk_add_f32 v[58:59], v[58:59], v[194:195] op_sel:[0,1] op_sel_hi:[1,1] neg_lo:[0,1] neg_hi:[0,1]
	v_pk_add_f32 v[60:61], v[60:61], v[194:195] op_sel:[0,1] op_sel_hi:[1,1] neg_lo:[0,1] neg_hi:[0,1]
	v_pk_add_f32 v[62:63], v[62:63], v[194:195] op_sel:[0,1] op_sel_hi:[1,1] neg_lo:[0,1] neg_hi:[0,1]
	v_pk_add_f32 v[64:65], v[64:65], v[194:195] op_sel:[0,1] op_sel_hi:[1,1] neg_lo:[0,1] neg_hi:[0,1]
	v_pk_add_f32 v[66:67], v[66:67], v[194:195] op_sel:[0,1] op_sel_hi:[1,1] neg_lo:[0,1] neg_hi:[0,1]
	v_pk_add_f32 v[36:37], v[36:37], v[194:195] op_sel:[0,1] op_sel_hi:[1,1] neg_lo:[0,1] neg_hi:[0,1]
	v_pk_add_f32 v[38:39], v[38:39], v[194:195] op_sel:[0,1] op_sel_hi:[1,1] neg_lo:[0,1] neg_hi:[0,1]
	v_pk_add_f32 v[40:41], v[40:41], v[194:195] op_sel:[0,1] op_sel_hi:[1,1] neg_lo:[0,1] neg_hi:[0,1]
	v_pk_add_f32 v[42:43], v[42:43], v[194:195] op_sel:[0,1] op_sel_hi:[1,1] neg_lo:[0,1] neg_hi:[0,1]
	v_pk_add_f32 v[44:45], v[44:45], v[194:195] op_sel:[0,1] op_sel_hi:[1,1] neg_lo:[0,1] neg_hi:[0,1]
	v_pk_add_f32 v[46:47], v[46:47], v[194:195] op_sel:[0,1] op_sel_hi:[1,1] neg_lo:[0,1] neg_hi:[0,1]
	v_pk_add_f32 v[48:49], v[48:49], v[194:195] op_sel:[0,1] op_sel_hi:[1,1] neg_lo:[0,1] neg_hi:[0,1]
	v_pk_add_f32 v[50:51], v[50:51], v[194:195] op_sel:[0,1] op_sel_hi:[1,1] neg_lo:[0,1] neg_hi:[0,1]
	v_exp_f32_e32 v52, v52
	v_exp_f32_e32 v53, v53
	v_exp_f32_e32 v54, v54
	v_add_f32_e32 v3, v53, v52
	v_exp_f32_e32 v55, v55
	v_add_f32_e32 v3, v54, v3
	v_exp_f32_e32 v56, v56
	v_add_f32_e32 v3, v55, v3
	v_exp_f32_e32 v57, v57
	v_add_f32_e32 v3, v56, v3
	v_exp_f32_e32 v58, v58
	v_add_f32_e32 v3, v57, v3
	v_exp_f32_e32 v59, v59
	v_add_f32_e32 v3, v58, v3
	v_exp_f32_e32 v60, v60
	v_add_f32_e32 v3, v59, v3
	v_exp_f32_e32 v61, v61
	v_add_f32_e32 v3, v60, v3
	v_exp_f32_e32 v62, v62
	v_add_f32_e32 v3, v61, v3
	v_exp_f32_e32 v63, v63
	v_add_f32_e32 v3, v62, v3
	v_exp_f32_e32 v64, v64
	v_add_f32_e32 v3, v63, v3
	v_exp_f32_e32 v65, v65
	v_add_f32_e32 v3, v64, v3
	v_exp_f32_e32 v66, v66
	v_add_f32_e32 v3, v65, v3
	v_exp_f32_e32 v67, v67
	v_add_f32_e32 v3, v66, v3
	v_exp_f32_e32 v36, v36
	v_add_f32_e32 v3, v67, v3
	v_exp_f32_e32 v37, v37
	v_add_f32_e32 v3, v36, v3
	v_exp_f32_e32 v38, v38
	v_add_f32_e32 v3, v37, v3
	v_exp_f32_e32 v39, v39
	v_add_f32_e32 v3, v38, v3
	v_exp_f32_e32 v40, v40
	v_add_f32_e32 v3, v39, v3
	v_exp_f32_e32 v41, v41
	v_add_f32_e32 v3, v40, v3
	v_exp_f32_e32 v42, v42
	v_add_f32_e32 v3, v41, v3
	v_exp_f32_e32 v43, v43
	v_add_f32_e32 v3, v42, v3
	v_exp_f32_e32 v44, v44
	v_add_f32_e32 v3, v43, v3
	v_exp_f32_e32 v45, v45
	v_add_f32_e32 v3, v44, v3
	v_exp_f32_e32 v46, v46
	v_add_f32_e32 v3, v45, v3
	v_exp_f32_e32 v47, v47
	v_add_f32_e32 v3, v46, v3
	v_exp_f32_e32 v48, v48
	v_add_f32_e32 v3, v47, v3
	v_exp_f32_e32 v49, v49
	v_add_f32_e32 v3, v48, v3
	v_exp_f32_e32 v50, v50
	v_add_f32_e32 v3, v49, v3
	v_exp_f32_e32 v51, v51
	v_add_f32_e32 v3, v50, v3
	v_add_u32_e32 v0, v183, v184
	v_add_u32_e32 v1, v183, v185
	v_add_f32_e32 v3, v51, v3
	v_add_f32_e32 v196, v3, v141
	ds_read_b64_tr_b16 v[72:73], v0 offset:40960
	ds_read_b64_tr_b16 v[74:75], v0 offset:41984
	ds_read_b64_tr_b16 v[76:77], v1 offset:40960
	ds_read_b64_tr_b16 v[78:79], v1 offset:41984
	v_cvt_pk_bf16_f32 v68, v52, v53
	v_cvt_pk_bf16_f32 v69, v54, v55
	v_cvt_pk_bf16_f32 v70, v56, v57
	v_cvt_pk_bf16_f32 v71, v58, v59
	s_waitcnt lgkmcnt(0)
	s_nop 0
	v_mfma_f32_32x32x16_bf16 v[20:35], v[72:75], v[68:71], v[20:35]
	v_mfma_f32_32x32x16_bf16 v[4:19], v[76:79], v[68:71], v[4:19]
	ds_read_b64_tr_b16 v[72:73], v0 offset:43008
	ds_read_b64_tr_b16 v[74:75], v0 offset:44032
	ds_read_b64_tr_b16 v[76:77], v1 offset:43008
	ds_read_b64_tr_b16 v[78:79], v1 offset:44032
	v_cvt_pk_bf16_f32 v68, v60, v61
	v_cvt_pk_bf16_f32 v69, v62, v63
	v_cvt_pk_bf16_f32 v70, v64, v65
	v_cvt_pk_bf16_f32 v71, v66, v67
	s_waitcnt lgkmcnt(0)
	s_nop 0
	v_mfma_f32_32x32x16_bf16 v[20:35], v[72:75], v[68:71], v[20:35]
	v_mfma_f32_32x32x16_bf16 v[4:19], v[76:79], v[68:71], v[4:19]
	ds_read_b64_tr_b16 v[72:73], v0 offset:45056
	ds_read_b64_tr_b16 v[74:75], v0 offset:46080
	ds_read_b64_tr_b16 v[76:77], v1 offset:45056
	ds_read_b64_tr_b16 v[78:79], v1 offset:46080
	v_cvt_pk_bf16_f32 v68, v36, v37
	v_cvt_pk_bf16_f32 v69, v38, v39
	v_cvt_pk_bf16_f32 v70, v40, v41
	v_cvt_pk_bf16_f32 v71, v42, v43
	s_waitcnt lgkmcnt(0)
	s_nop 0
	v_mfma_f32_32x32x16_bf16 v[20:35], v[72:75], v[68:71], v[20:35]
	v_mfma_f32_32x32x16_bf16 v[4:19], v[76:79], v[68:71], v[4:19]
	ds_read_b64_tr_b16 v[72:73], v0 offset:47104
	ds_read_b64_tr_b16 v[74:75], v0 offset:48128
	ds_read_b64_tr_b16 v[76:77], v1 offset:47104
	ds_read_b64_tr_b16 v[78:79], v1 offset:48128
	v_cvt_pk_bf16_f32 v68, v44, v45
	v_cvt_pk_bf16_f32 v69, v46, v47
	v_cvt_pk_bf16_f32 v70, v48, v49
	v_cvt_pk_bf16_f32 v71, v50, v51
	s_waitcnt lgkmcnt(0)
	s_nop 0
	v_mfma_f32_32x32x16_bf16 v[20:35], v[72:75], v[68:71], v[20:35]
	v_mfma_f32_32x32x16_bf16 v[4:19], v[76:79], v[68:71], v[4:19]
